# v54: UP K-loop issues its LDS-DMA loads before the ds_reads of the same interval (earlier issue = more latency slack)
# baseline (speedup 1.0000x reference)
; #define PG8_STAGE(bufoff, gbase) do { _Pragma("unroll") for (int _i = 0; _i < 2; ++_i) \
;         __builtin_amdgcn_global_load_lds((const unsigned*)((const char*)(gbase) + voff[_i]), (LAS unsigned*)(lds + (bufoff) + ldsw + _i * 8192), 16, 0, 0); } while (0)
; #define PG8_LDA(dst, b, h) do { _Pragma("unroll") for (int m = 0; m < 4; ++m) _Pragma("unroll") for (int k = 0; k < 2; ++k) dst[m][k] = *(const LAS bf16x8*)(lds + PG8_SA(b, h) + aoff + m * 2048 + k * 1024); } while (0)
; #define PG8_LDB(dst, b, h) do { _Pragma("unroll") for (int n = 0; n < 2; ++n) _Pragma("unroll") for (int k = 0; k < 2; ++k) dst[n][k] = *(const LAS bf16x8*)(lds + PG8_SB(b, h) + boff + n * 2048 + k * 1024); } while (0)
; #define PG8_MMA(ai, bj, At, Bt) do { __builtin_amdgcn_s_setprio(1); _Pragma("unroll") for (int m = 0; m < 4; ++m) _Pragma("unroll") for (int n = 0; n < 2; ++n) _Pragma("unroll") for (int k = 0; k < 2; ++k) \
;         acc[ai][bj][m][n] = __builtin_amdgcn_mfma_f32_16x16x32_bf16(Bt[n][k], At[m][k], acc[ai][bj][m][n], 0, 0, 0); __builtin_amdgcn_s_setprio(0); } while (0)
; #define PG8_WAIT_V(n) asm volatile("s_waitcnt vmcnt(" #n ")" ::: "memory")
; #define PG8_WAIT_L(n) asm volatile("s_waitcnt lgkmcnt(" #n ")" ::: "memory")
; #define PG8_BAR __builtin_amdgcn_s_barrier()
; #define PG8_SCHED __builtin_amdgcn_sched_barrier(0)
; template <int EPI> ...
;     ...
;         for (int t = 0; t < cnk; t += 2) {
;             const bool last = (t == cnk - 2);
;             const char* a1 = cA + (size_t)(t + 1) * kstep;
;             const char* a2 = last ? nA : cA + (size_t)(t + 2) * kstep; const char* b2 = last ? nB : cB + (size_t)(t + 2) * kstep;
;             const char* a3 = a2 + kstep; const char* b3 = b2 + kstep;
;             PG8_LDB(B0, 0, 0); PG8_LDB(B1, 0, 1); PG8_SCHED; PG8_LDA(At, 0, 0); PG8_STAGE(PG8_SA(1, 1), a1 + hstep);
;             PG8_WAIT_V(8); PG8_WAIT_L(0); PG8_BAR; PG8_MMA(0, 0, At, B0); PG8_MMA(0, 1, At, B1); PG8_BAR; PG8_SCHED;
.LBB0_970:
	s_add_u32 s58, s56, 0xfffc0080
	s_addc_u32 s59, s57, -1
	s_cmp_eq_u32 s83, 12
	s_cselect_b32 s61, s19, s59
	s_cselect_b32 s60, s49, s58
	s_cselect_b32 s59, s47, s63
	s_cselect_b32 s58, s55, s62
	v_lshl_add_u64 v[226:227], s[56:57], 0, v[206:207]
	s_add_i32 m0, s66, 0xc000
	s_nop 0
	global_load_lds_dwordx4 v[226:227], off
	v_lshl_add_u64 v[226:227], s[56:57], 0, v[208:209]
	s_add_i32 m0, s66, 0xe000
	s_nop 0
	global_load_lds_dwordx4 v[226:227], off
	ds_read_b128 v[38:41], v189
	ds_read_b128 v[42:45], v189 offset:1024
	ds_read_b128 v[46:49], v189 offset:2048
	ds_read_b128 v[50:53], v189 offset:3072
	ds_read_b128 v[54:57], v191
	ds_read_b128 v[58:61], v191 offset:1024
	ds_read_b128 v[66:69], v191 offset:2048
	ds_read_b128 v[70:73], v191 offset:3072
	ds_read_b128 v[162:165], v193
	ds_read_b128 v[166:169], v193 offset:1024
	ds_read_b128 v[170:173], v193 offset:2048
	ds_read_b128 v[174:177], v193 offset:3072
	ds_read_b128 v[178:181], v193 offset:4096
	ds_read_b128 v[214:217], v193 offset:5120
	ds_read_b128 v[218:221], v193 offset:6144
	ds_read_b128 v[222:225], v193 offset:7168
	s_cmp_lg_u32 s83, -2
	s_cbranch_scc1 .Lup_strict_0
	s_cmp_lt_u32 s70, 2
	s_cbranch_scc1 .Lup_strict_0
	s_waitcnt vmcnt(24)
	s_branch .Lup_wdone_0

; #define PG8_STAGE(bufoff, gbase) do { _Pragma("unroll") for (int _i = 0; _i < 2; ++_i) \
;         __builtin_amdgcn_global_load_lds((const unsigned*)((const char*)(gbase) + voff[_i]), (LAS unsigned*)(lds + (bufoff) + ldsw + _i * 8192), 16, 0, 0); } while (0)
; #define PG8_LDA(dst, b, h) do { _Pragma("unroll") for (int m = 0; m < 4; ++m) _Pragma("unroll") for (int k = 0; k < 2; ++k) dst[m][k] = *(const LAS bf16x8*)(lds + PG8_SA(b, h) + aoff + m * 2048 + k * 1024); } while (0)
; #define PG8_MMA(ai, bj, At, Bt) do { __builtin_amdgcn_s_setprio(1); _Pragma("unroll") for (int m = 0; m < 4; ++m) _Pragma("unroll") for (int n = 0; n < 2; ++n) _Pragma("unroll") for (int k = 0; k < 2; ++k) \
;         acc[ai][bj][m][n] = __builtin_amdgcn_mfma_f32_16x16x32_bf16(Bt[n][k], At[m][k], acc[ai][bj][m][n], 0, 0, 0); __builtin_amdgcn_s_setprio(0); } while (0)
; #define PG8_WAIT_V(n) asm volatile("s_waitcnt vmcnt(" #n ")" ::: "memory")
; #define PG8_WAIT_L(n) asm volatile("s_waitcnt lgkmcnt(" #n ")" ::: "memory")
; #define PG8_BAR __builtin_amdgcn_s_barrier()
; #define PG8_SCHED __builtin_amdgcn_sched_barrier(0)
; template <int EPI> ...
;     ...
;             PG8_WAIT_V(8); PG8_WAIT_L(0); PG8_BAR; PG8_MMA(0, 0, At, B0); PG8_MMA(0, 1, At, B1); PG8_BAR; PG8_SCHED;
;             PG8_LDA(At, 0, 1); PG8_STAGE(PG8_SB(0, 0), b2); PG8_STAGE(PG8_SB(0, 1), b2 + hstep); PG8_STAGE(PG8_SA(0, 0), a2);
;             PG8_WAIT_V(8); PG8_WAIT_L(0); PG8_BAR; PG8_MMA(1, 0, At, B0); PG8_MMA(1, 1, At, B1); PG8_BAR; PG8_SCHED;
.Lup_wdone_0:
	s_waitcnt lgkmcnt(0)
	s_barrier
	s_setprio 1
	s_waitcnt lgkmcnt(0)
	v_mfma_f32_16x16x32_bf16 v[150:153], v[38:41], v[162:165], v[150:153]
	v_mfma_f32_16x16x32_bf16 v[158:161], v[46:49], v[162:165], v[158:161]
	v_mfma_f32_16x16x32_bf16 v[134:137], v[38:41], v[170:173], v[134:137]
	v_mfma_f32_16x16x32_bf16 v[142:145], v[46:49], v[170:173], v[142:145]
	v_mfma_f32_16x16x32_bf16 v[118:121], v[38:41], v[178:181], v[118:121]
	v_mfma_f32_16x16x32_bf16 v[126:129], v[46:49], v[178:181], v[126:129]
	v_mfma_f32_16x16x32_bf16 v[110:113], v[38:41], v[218:221], v[110:113]
	v_mfma_f32_16x16x32_bf16 v[106:109], v[46:49], v[218:221], v[106:109]
	v_mfma_f32_16x16x32_bf16 v[150:153], v[42:45], v[166:169], v[150:153]
	v_mfma_f32_16x16x32_bf16 v[158:161], v[50:53], v[166:169], v[158:161]
	v_mfma_f32_16x16x32_bf16 v[134:137], v[42:45], v[174:177], v[134:137]
	v_mfma_f32_16x16x32_bf16 v[142:145], v[50:53], v[174:177], v[142:145]
	v_mfma_f32_16x16x32_bf16 v[118:121], v[42:45], v[214:217], v[118:121]
	v_mfma_f32_16x16x32_bf16 v[126:129], v[50:53], v[214:217], v[126:129]
	v_mfma_f32_16x16x32_bf16 v[110:113], v[42:45], v[222:225], v[110:113]
	v_mfma_f32_16x16x32_bf16 v[106:109], v[50:53], v[222:225], v[106:109]
	s_setprio 0
	s_setprio 1
	v_mfma_f32_16x16x32_bf16 v[146:149], v[54:57], v[162:165], v[146:149]
	v_mfma_f32_16x16x32_bf16 v[154:157], v[66:69], v[162:165], v[154:157]
	v_mfma_f32_16x16x32_bf16 v[130:133], v[54:57], v[170:173], v[130:133]
	v_mfma_f32_16x16x32_bf16 v[138:141], v[66:69], v[170:173], v[138:141]
	v_mfma_f32_16x16x32_bf16 v[114:117], v[54:57], v[178:181], v[114:117]
	v_mfma_f32_16x16x32_bf16 v[122:125], v[66:69], v[178:181], v[122:125]
	v_mfma_f32_16x16x32_bf16 v[102:105], v[54:57], v[218:221], v[102:105]
	v_mfma_f32_16x16x32_bf16 v[98:101], v[66:69], v[218:221], v[98:101]
	v_mfma_f32_16x16x32_bf16 v[146:149], v[58:61], v[166:169], v[146:149]
	v_mfma_f32_16x16x32_bf16 v[154:157], v[70:73], v[166:169], v[154:157]
	v_mfma_f32_16x16x32_bf16 v[130:133], v[58:61], v[174:177], v[130:133]
	v_mfma_f32_16x16x32_bf16 v[138:141], v[70:73], v[174:177], v[138:141]
	v_mfma_f32_16x16x32_bf16 v[114:117], v[58:61], v[214:217], v[114:117]
	v_mfma_f32_16x16x32_bf16 v[122:125], v[70:73], v[214:217], v[122:125]
	v_mfma_f32_16x16x32_bf16 v[102:105], v[58:61], v[222:225], v[102:105]
	v_mfma_f32_16x16x32_bf16 v[98:101], v[70:73], v[222:225], v[98:101]
	s_setprio 0
	s_barrier
	s_add_i32 s84, s75, s65
	v_lshl_add_u64 v[230:231], s[58:59], 0, v[194:195]
	s_mov_b32 m0, s84
	s_nop 0
	global_load_lds_dwordx4 v[230:231], off
	s_add_i32 m0, s84, 0x2000
	s_add_u32 s84, s58, 0x40000
	v_lshl_add_u64 v[232:233], s[58:59], 0, v[196:197]
	s_addc_u32 s85, s59, 0
	s_add_i32 s86, s76, s65
	global_load_lds_dwordx4 v[232:233], off
	v_lshl_add_u64 v[226:227], s[84:85], 0, v[194:195]
	s_mov_b32 m0, s86
	v_lshl_add_u64 v[234:235], s[60:61], 0, v[194:195]
	global_load_lds_dwordx4 v[226:227], off
	v_lshl_add_u64 v[226:227], s[84:85], 0, v[196:197]
	s_add_i32 m0, s86, 0x2000
	v_lshl_add_u64 v[236:237], s[60:61], 0, v[196:197]
	global_load_lds_dwordx4 v[226:227], off
	s_mov_b32 m0, s66
	s_nop 0
	global_load_lds_dwordx4 v[234:235], off
	s_mov_b32 m0, s67
	s_nop 0
	global_load_lds_dwordx4 v[236:237], off
	ds_read_b128 v[162:165], v193 offset:16384
	ds_read_b128 v[166:169], v193 offset:17408
	ds_read_b128 v[170:173], v193 offset:18432
	ds_read_b128 v[174:177], v193 offset:19456
	ds_read_b128 v[178:181], v193 offset:20480
	ds_read_b128 v[214:217], v193 offset:21504
	ds_read_b128 v[218:221], v193 offset:22528
	ds_read_b128 v[222:225], v193 offset:23552
	s_cmp_lg_u32 s83, -2
	s_cbranch_scc1 .Lup_strict_1
	s_cmp_lt_u32 s70, 2
	s_cbranch_scc1 .Lup_strict_1
	s_waitcnt vmcnt(24)
	s_branch .Lup_wdone_1

; #define PG8_STAGE(bufoff, gbase) do { _Pragma("unroll") for (int _i = 0; _i < 2; ++_i) \
;         __builtin_amdgcn_global_load_lds((const unsigned*)((const char*)(gbase) + voff[_i]), (LAS unsigned*)(lds + (bufoff) + ldsw + _i * 8192), 16, 0, 0); } while (0)
; #define PG8_LDA(dst, b, h) do { _Pragma("unroll") for (int m = 0; m < 4; ++m) _Pragma("unroll") for (int k = 0; k < 2; ++k) dst[m][k] = *(const LAS bf16x8*)(lds + PG8_SA(b, h) + aoff + m * 2048 + k * 1024); } while (0)
; #define PG8_LDB(dst, b, h) do { _Pragma("unroll") for (int n = 0; n < 2; ++n) _Pragma("unroll") for (int k = 0; k < 2; ++k) dst[n][k] = *(const LAS bf16x8*)(lds + PG8_SB(b, h) + boff + n * 2048 + k * 1024); } while (0)
; #define PG8_MMA(ai, bj, At, Bt) do { __builtin_amdgcn_s_setprio(1); _Pragma("unroll") for (int m = 0; m < 4; ++m) _Pragma("unroll") for (int n = 0; n < 2; ++n) _Pragma("unroll") for (int k = 0; k < 2; ++k) \
;         acc[ai][bj][m][n] = __builtin_amdgcn_mfma_f32_16x16x32_bf16(Bt[n][k], At[m][k], acc[ai][bj][m][n], 0, 0, 0); __builtin_amdgcn_s_setprio(0); } while (0)
; #define PG8_WAIT_V(n) asm volatile("s_waitcnt vmcnt(" #n ")" ::: "memory")
; #define PG8_WAIT_L(n) asm volatile("s_waitcnt lgkmcnt(" #n ")" ::: "memory")
; #define PG8_BAR __builtin_amdgcn_s_barrier()
; #define PG8_SCHED __builtin_amdgcn_sched_barrier(0)
; template <int EPI> ...
;     ...
;             PG8_WAIT_V(8); PG8_WAIT_L(0); PG8_BAR; PG8_MMA(1, 0, At, B0); PG8_MMA(1, 1, At, B1); PG8_BAR; PG8_SCHED;
;             PG8_LDB(B0, 1, 0); PG8_LDB(B1, 1, 1); PG8_SCHED; PG8_LDA(At, 1, 0); PG8_STAGE(PG8_SA(0, 1), a2 + hstep);
;             PG8_WAIT_V(8); PG8_WAIT_L(0); PG8_BAR; PG8_MMA(0, 0, At, B0); PG8_MMA(0, 1, At, B1); PG8_BAR; PG8_SCHED;
.Lup_wdone_1:
	s_waitcnt lgkmcnt(0)
	s_barrier
	s_setprio 1
	s_waitcnt lgkmcnt(0)
	v_mfma_f32_16x16x32_bf16 v[86:89], v[38:41], v[162:165], v[86:89]
	v_mfma_f32_16x16x32_bf16 v[94:97], v[46:49], v[162:165], v[94:97]
	v_mfma_f32_16x16x32_bf16 v[62:65], v[38:41], v[170:173], v[62:65]
	v_mfma_f32_16x16x32_bf16 v[78:81], v[46:49], v[170:173], v[78:81]
	v_mfma_f32_16x16x32_bf16 v[22:25], v[38:41], v[178:181], v[22:25]
	v_mfma_f32_16x16x32_bf16 v[30:33], v[46:49], v[178:181], v[30:33]
	v_mfma_f32_16x16x32_bf16 v[14:17], v[38:41], v[218:221], v[14:17]
	v_mfma_f32_16x16x32_bf16 v[10:13], v[46:49], v[218:221], v[10:13]
	v_mfma_f32_16x16x32_bf16 v[86:89], v[42:45], v[166:169], v[86:89]
	v_mfma_f32_16x16x32_bf16 v[94:97], v[50:53], v[166:169], v[94:97]
	v_mfma_f32_16x16x32_bf16 v[62:65], v[42:45], v[174:177], v[62:65]
	v_mfma_f32_16x16x32_bf16 v[78:81], v[50:53], v[174:177], v[78:81]
	v_mfma_f32_16x16x32_bf16 v[22:25], v[42:45], v[214:217], v[22:25]
	v_mfma_f32_16x16x32_bf16 v[30:33], v[50:53], v[214:217], v[30:33]
	v_mfma_f32_16x16x32_bf16 v[14:17], v[42:45], v[222:225], v[14:17]
	v_mfma_f32_16x16x32_bf16 v[10:13], v[50:53], v[222:225], v[10:13]
	s_setprio 0
	s_setprio 1
	v_mfma_f32_16x16x32_bf16 v[34:37], v[54:57], v[170:173], v[34:37]
	v_mfma_f32_16x16x32_bf16 v[18:21], v[54:57], v[178:181], v[18:21]
	v_mfma_f32_16x16x32_bf16 v[26:29], v[66:69], v[178:181], v[26:29]
	v_mfma_f32_16x16x32_bf16 v[6:9], v[54:57], v[218:221], v[6:9]
	v_mfma_f32_16x16x32_bf16 v[2:5], v[66:69], v[218:221], v[2:5]
	v_mfma_f32_16x16x32_bf16 v[38:41], v[54:57], v[162:165], v[82:85]
	v_mfma_f32_16x16x32_bf16 v[42:45], v[66:69], v[162:165], v[90:93]
	v_mfma_f32_16x16x32_bf16 v[34:37], v[58:61], v[174:177], v[34:37]
	v_mfma_f32_16x16x32_bf16 v[46:49], v[66:69], v[170:173], v[74:77]
	v_mfma_f32_16x16x32_bf16 v[18:21], v[58:61], v[214:217], v[18:21]
	v_mfma_f32_16x16x32_bf16 v[26:29], v[70:73], v[214:217], v[26:29]
	v_mfma_f32_16x16x32_bf16 v[6:9], v[58:61], v[222:225], v[6:9]
	v_mfma_f32_16x16x32_bf16 v[2:5], v[70:73], v[222:225], v[2:5]
	v_mfma_f32_16x16x32_bf16 v[38:41], v[58:61], v[166:169], v[38:41]
	v_mfma_f32_16x16x32_bf16 v[42:45], v[70:73], v[166:169], v[42:45]
	v_mfma_f32_16x16x32_bf16 v[46:49], v[70:73], v[174:177], v[46:49]
	s_setprio 0
	s_barrier
	s_add_i32 s84, 0, 0x18000
	s_add_i32 s85, 0, 0x1c000
	v_add_u32_e32 v66, s84, v183
	v_add_u32_e32 v74, s85, v183
	s_add_u32 s60, s60, 0x40000
	s_addc_u32 s61, s61, 0
	s_mov_b32 m0, s68
	v_lshl_add_u64 v[226:227], s[60:61], 0, v[194:195]
	global_load_lds_dwordx4 v[226:227], off
	v_lshl_add_u64 v[226:227], s[60:61], 0, v[196:197]
	s_mov_b32 m0, s69
	s_nop 0
	global_load_lds_dwordx4 v[226:227], off
	ds_read_b128 v[50:53], v66
	ds_read_b128 v[54:57], v66 offset:1024
	ds_read_b128 v[58:61], v66 offset:2048
	ds_read_b128 v[66:69], v66 offset:3072
	ds_read_b128 v[70:73], v74
	ds_read_b128 v[162:165], v74 offset:1024
	ds_read_b128 v[166:169], v74 offset:2048
	ds_read_b128 v[170:173], v74 offset:3072
	ds_read_b128 v[74:77], v193 offset:32768
	ds_read_b128 v[82:85], v193 offset:33792
	ds_read_b128 v[90:93], v193 offset:34816
	ds_read_b128 v[174:177], v193 offset:35840
	ds_read_b128 v[178:181], v193 offset:36864
	ds_read_b128 v[214:217], v193 offset:37888
	ds_read_b128 v[218:221], v193 offset:38912
	ds_read_b128 v[222:225], v193 offset:39936
	s_waitcnt vmcnt(8)
	s_waitcnt lgkmcnt(0)
	s_barrier
	s_setprio 1
	s_waitcnt lgkmcnt(0)
	v_mfma_f32_16x16x32_bf16 v[150:153], v[50:53], v[74:77], v[150:153]
	v_mfma_f32_16x16x32_bf16 v[158:161], v[58:61], v[74:77], v[158:161]
	v_mfma_f32_16x16x32_bf16 v[134:137], v[50:53], v[90:93], v[134:137]
	v_mfma_f32_16x16x32_bf16 v[142:145], v[58:61], v[90:93], v[142:145]
	v_mfma_f32_16x16x32_bf16 v[118:121], v[50:53], v[178:181], v[118:121]
	v_mfma_f32_16x16x32_bf16 v[126:129], v[58:61], v[178:181], v[126:129]
	v_mfma_f32_16x16x32_bf16 v[110:113], v[50:53], v[218:221], v[110:113]
	v_mfma_f32_16x16x32_bf16 v[106:109], v[58:61], v[218:221], v[106:109]
	v_mfma_f32_16x16x32_bf16 v[150:153], v[54:57], v[82:85], v[150:153]
	v_mfma_f32_16x16x32_bf16 v[158:161], v[66:69], v[82:85], v[158:161]
	v_mfma_f32_16x16x32_bf16 v[134:137], v[54:57], v[174:177], v[134:137]
	v_mfma_f32_16x16x32_bf16 v[142:145], v[66:69], v[174:177], v[142:145]
	v_mfma_f32_16x16x32_bf16 v[118:121], v[54:57], v[214:217], v[118:121]
	v_mfma_f32_16x16x32_bf16 v[126:129], v[66:69], v[214:217], v[126:129]
	v_mfma_f32_16x16x32_bf16 v[110:113], v[54:57], v[222:225], v[110:113]
	v_mfma_f32_16x16x32_bf16 v[106:109], v[66:69], v[222:225], v[106:109]
	s_setprio 0
	s_setprio 1
	v_mfma_f32_16x16x32_bf16 v[146:149], v[70:73], v[74:77], v[146:149]
	v_mfma_f32_16x16x32_bf16 v[74:77], v[166:169], v[74:77], v[154:157]
	v_mfma_f32_16x16x32_bf16 v[154:157], v[170:173], v[82:85], v[74:77]
	v_mfma_f32_16x16x32_bf16 v[74:77], v[70:73], v[90:93], v[130:133]
	v_mfma_f32_16x16x32_bf16 v[130:133], v[162:165], v[174:177], v[74:77]
	v_mfma_f32_16x16x32_bf16 v[74:77], v[166:169], v[90:93], v[138:141]
	v_mfma_f32_16x16x32_bf16 v[138:141], v[170:173], v[174:177], v[74:77]
	v_mfma_f32_16x16x32_bf16 v[74:77], v[70:73], v[178:181], v[114:117]
	v_mfma_f32_16x16x32_bf16 v[114:117], v[162:165], v[214:217], v[74:77]
	v_mfma_f32_16x16x32_bf16 v[74:77], v[166:169], v[178:181], v[122:125]
	v_mfma_f32_16x16x32_bf16 v[122:125], v[170:173], v[214:217], v[74:77]
	v_mfma_f32_16x16x32_bf16 v[74:77], v[70:73], v[218:221], v[102:105]
	v_mfma_f32_16x16x32_bf16 v[102:105], v[162:165], v[222:225], v[74:77]
	v_mfma_f32_16x16x32_bf16 v[74:77], v[166:169], v[218:221], v[98:101]
	v_mfma_f32_16x16x32_bf16 v[146:149], v[162:165], v[82:85], v[146:149]
	v_mfma_f32_16x16x32_bf16 v[98:101], v[170:173], v[222:225], v[74:77]
	s_setprio 0
	s_barrier
; #define PG8_STAGE(bufoff, gbase) do { _Pragma("unroll") for (int _i = 0; _i < 2; ++_i) \
;         __builtin_amdgcn_global_load_lds((const unsigned*)((const char*)(gbase) + voff[_i]), (LAS unsigned*)(lds + (bufoff) + ldsw + _i * 8192), 16, 0, 0); } while (0)
; #define PG8_LDA(dst, b, h) do { _Pragma("unroll") for (int m = 0; m < 4; ++m) _Pragma("unroll") for (int k = 0; k < 2; ++k) dst[m][k] = *(const LAS bf16x8*)(lds + PG8_SA(b, h) + aoff + m * 2048 + k * 1024); } while (0)
; #define PG8_MMA(ai, bj, At, Bt) do { __builtin_amdgcn_s_setprio(1); _Pragma("unroll") for (int m = 0; m < 4; ++m) _Pragma("unroll") for (int n = 0; n < 2; ++n) _Pragma("unroll") for (int k = 0; k < 2; ++k) \
;         acc[ai][bj][m][n] = __builtin_amdgcn_mfma_f32_16x16x32_bf16(Bt[n][k], At[m][k], acc[ai][bj][m][n], 0, 0, 0); __builtin_amdgcn_s_setprio(0); } while (0)
; #define PG8_WAIT_V(n) asm volatile("s_waitcnt vmcnt(" #n ")" ::: "memory")
; #define PG8_WAIT_L(n) asm volatile("s_waitcnt lgkmcnt(" #n ")" ::: "memory")
; #define PG8_BAR __builtin_amdgcn_s_barrier()
; #define PG8_SCHED __builtin_amdgcn_sched_barrier(0)
; template <int EPI> ...
;     ...
;             PG8_WAIT_V(8); PG8_WAIT_L(0); PG8_BAR; PG8_MMA(0, 0, At, B0); PG8_MMA(0, 1, At, B1); PG8_BAR; PG8_SCHED;
;             PG8_LDA(At, 1, 1); PG8_STAGE(PG8_SB(1, 0), b3); PG8_STAGE(PG8_SB(1, 1), b3 + hstep); PG8_STAGE(PG8_SA(1, 0), a3);
;             PG8_WAIT_V(8); PG8_WAIT_L(0); PG8_BAR; PG8_MMA(1, 0, At, B0); PG8_MMA(1, 1, At, B1); PG8_BAR; PG8_SCHED;
;         }
	s_add_i32 s60, s84, s65
	v_lshl_add_u64 v[82:83], v[230:231], 0, s[26:27]
	s_mov_b32 m0, s60
	s_nop 0
	global_load_lds_dwordx4 v[82:83], off
	s_add_i32 m0, s60, 0x2000
	s_add_u32 s58, s58, 0x40080
	v_lshl_add_u64 v[82:83], v[232:233], 0, s[26:27]
	s_addc_u32 s59, s59, 0
	s_add_i32 s60, s85, s65
	global_load_lds_dwordx4 v[82:83], off
	v_lshl_add_u64 v[82:83], s[58:59], 0, v[194:195]
	s_mov_b32 m0, s60
	s_nop 0
	global_load_lds_dwordx4 v[82:83], off
	v_lshl_add_u64 v[82:83], s[58:59], 0, v[196:197]
	s_add_i32 m0, s60, 0x2000
	s_nop 0
	global_load_lds_dwordx4 v[82:83], off
	v_lshl_add_u64 v[82:83], v[234:235], 0, s[26:27]
	s_mov_b32 m0, s72
	s_nop 0
	global_load_lds_dwordx4 v[82:83], off
	v_lshl_add_u64 v[82:83], v[236:237], 0, s[26:27]
	s_mov_b32 m0, s73
	s_nop 0
	global_load_lds_dwordx4 v[82:83], off
	ds_read_b128 v[74:77], v193 offset:49152
	ds_read_b128 v[90:93], v193 offset:50176
	ds_read_b128 v[174:177], v193 offset:51200
	ds_read_b128 v[178:181], v193 offset:52224
	ds_read_b128 v[214:217], v193 offset:53248
	ds_read_b128 v[218:221], v193 offset:54272
	ds_read_b128 v[222:225], v193 offset:55296
	ds_read_b128 v[226:229], v193 offset:56320
	s_waitcnt vmcnt(8)
	s_waitcnt lgkmcnt(0)
	s_barrier
	s_setprio 1
	s_waitcnt lgkmcnt(0)
	v_mfma_f32_16x16x32_bf16 v[82:85], v[50:53], v[74:77], v[86:89]
	v_mfma_f32_16x16x32_bf16 v[86:89], v[54:57], v[90:93], v[82:85]
	v_mfma_f32_16x16x32_bf16 v[82:85], v[58:61], v[74:77], v[94:97]
	v_mfma_f32_16x16x32_bf16 v[62:65], v[50:53], v[174:177], v[62:65]
	v_mfma_f32_16x16x32_bf16 v[78:81], v[58:61], v[174:177], v[78:81]
	v_mfma_f32_16x16x32_bf16 v[22:25], v[50:53], v[214:217], v[22:25]
	v_mfma_f32_16x16x32_bf16 v[30:33], v[58:61], v[214:217], v[30:33]
	v_mfma_f32_16x16x32_bf16 v[14:17], v[50:53], v[222:225], v[14:17]
	v_mfma_f32_16x16x32_bf16 v[10:13], v[58:61], v[222:225], v[10:13]
	v_mfma_f32_16x16x32_bf16 v[94:97], v[66:69], v[90:93], v[82:85]
	v_mfma_f32_16x16x32_bf16 v[62:65], v[54:57], v[178:181], v[62:65]
	v_mfma_f32_16x16x32_bf16 v[78:81], v[66:69], v[178:181], v[78:81]
	v_mfma_f32_16x16x32_bf16 v[22:25], v[54:57], v[218:221], v[22:25]
	v_mfma_f32_16x16x32_bf16 v[30:33], v[66:69], v[218:221], v[30:33]
	v_mfma_f32_16x16x32_bf16 v[14:17], v[54:57], v[226:229], v[14:17]
	v_mfma_f32_16x16x32_bf16 v[10:13], v[66:69], v[226:229], v[10:13]
	s_setprio 0
	s_setprio 1
	v_mfma_f32_16x16x32_bf16 v[38:41], v[70:73], v[74:77], v[38:41]
	v_mfma_f32_16x16x32_bf16 v[82:85], v[162:165], v[90:93], v[38:41]
	v_mfma_f32_16x16x32_bf16 v[38:41], v[166:169], v[74:77], v[42:45]
	v_mfma_f32_16x16x32_bf16 v[90:93], v[170:173], v[90:93], v[38:41]
	v_mfma_f32_16x16x32_bf16 v[34:37], v[70:73], v[174:177], v[34:37]
	v_mfma_f32_16x16x32_bf16 v[38:41], v[166:169], v[174:177], v[46:49]
	v_mfma_f32_16x16x32_bf16 v[18:21], v[70:73], v[214:217], v[18:21]
	v_mfma_f32_16x16x32_bf16 v[26:29], v[166:169], v[214:217], v[26:29]
	v_mfma_f32_16x16x32_bf16 v[6:9], v[70:73], v[222:225], v[6:9]
	v_mfma_f32_16x16x32_bf16 v[2:5], v[166:169], v[222:225], v[2:5]
	v_mfma_f32_16x16x32_bf16 v[34:37], v[162:165], v[178:181], v[34:37]
	v_mfma_f32_16x16x32_bf16 v[74:77], v[170:173], v[178:181], v[38:41]
	v_mfma_f32_16x16x32_bf16 v[18:21], v[162:165], v[218:221], v[18:21]
	v_mfma_f32_16x16x32_bf16 v[26:29], v[170:173], v[218:221], v[26:29]
	v_mfma_f32_16x16x32_bf16 v[6:9], v[162:165], v[226:229], v[6:9]
	v_mfma_f32_16x16x32_bf16 v[2:5], v[170:173], v[226:229], v[2:5]
	s_setprio 0
	s_barrier
	s_add_i32 s83, s83, 2
	s_add_u32 s56, s56, 0x100
	s_addc_u32 s57, s57, 0
	s_add_u32 s62, s62, 0x100
	s_addc_u32 s63, s63, 0
	s_cmp_gt_u32 s83, 13
	s_cbranch_scc0 .LBB0_970
	s_and_b64 vcc, exec, s[28:29]
	s_cbranch_vccz .LBB0_973
	s_barrier
